# v54 + next unit's beta/decay-logit rows touched into L2 together with its conv rows
# baseline (speedup 1.0000x reference)
; __device__ __forceinline__ void gdn_local_unit(LAS unsigned char* lds, const GdnP& P, int unit, const int tid, const int pf) {
;     ...
;         for (int r = 0; r < 11; ++r) { const int tt = t0 - 3 + r; raw[r] = (u32x4){0u, 0u, 0u, 0u};
;             if (tt >= 0) raw[r] = *(const u32x4*)(P.proj + (size_t)(row0 + tt) * NIN + C_GDN + col);
;             else if (n > 0) raw[r] = *(const u32x4*)(P.halo + ((size_t)(cn - 1) * 3 + (tt + 3)) * 3072 + col); }
;     ...
;     else if (tid < 192) { const int t = tid - 128; const float bl = P.baf[(size_t)(row0 + t) * 16 + h], al = P.baf[(size_t)(row0 + t) * 16 + 8 + h];
.LBB0_1010:
	s_waitcnt lgkmcnt(0)
	s_barrier
	v_readlane_b32 s0, v253, 16
	s_add_i32 s0, s80, s0
	s_cmpk_gt_i32 s0, 0x7ff
	s_cbranch_scc1 .Lcpf_skip
	s_mov_b64 s[40:41], exec
	s_and_b64 exec, exec, s[76:77]
	s_cbranch_execz .Lcpf_done
	s_ashr_i32 s1, s0, 3
	s_and_b32 s2, s0, 7
	s_lshl_b32 s1, s1, 6
	v_lshl_or_b32 v246, s2, 7, v99
	v_mov_b32_e32 v247, 0
	v_add_u32_e32 v248, s1, v169
	v_mov_b64_e32 v[250:251], s[68:69]
	s_mov_b64 s[62:63], 0x5a00
	v_mad_i64_i32 v[250:251], s[42:43], v248, s87, v[250:251]
	v_lshl_add_u64 v[250:251], v[246:247], 1, v[250:251]
	s_mov_b64 s[2:3], 0x1000
	v_lshl_add_u64 v[250:251], v[250:251], 0, s[2:3]
	global_load_dword v249, v[250:251], off offset:2048
	v_lshl_add_u64 v[250:251], v[250:251], 0, s[62:63]
	global_load_dword v249, v[250:251], off offset:2048
	v_lshl_add_u64 v[250:251], v[250:251], 0, s[62:63]
	global_load_dword v249, v[250:251], off offset:2048
	v_lshl_add_u64 v[250:251], v[250:251], 0, s[62:63]
	global_load_dword v249, v[250:251], off offset:2048
	v_lshl_add_u64 v[250:251], v[250:251], 0, s[62:63]
	global_load_dword v249, v[250:251], off offset:2048
	v_lshl_add_u64 v[250:251], v[250:251], 0, s[62:63]
	global_load_dword v249, v[250:251], off offset:2048
	v_lshl_add_u64 v[250:251], v[250:251], 0, s[62:63]
	global_load_dword v249, v[250:251], off offset:2048
	v_lshl_add_u64 v[250:251], v[250:251], 0, s[62:63]
	global_load_dword v249, v[250:251], off offset:2048
	v_lshl_add_u64 v[250:251], v[250:251], 0, s[62:63]
	global_load_dword v249, v[250:251], off offset:2048
	v_lshl_add_u64 v[250:251], v[250:251], 0, s[62:63]
	global_load_dword v249, v[250:251], off offset:2048
	v_lshl_add_u64 v[250:251], v[250:251], 0, s[62:63]
	global_load_dword v249, v[250:251], off offset:2048
	v_add_u32_e32 v246, s1, v103
	v_lshlrev_b64 v[246:247], 6, v[246:247]
	v_lshl_add_u64 v[246:247], s[72:73], 0, v[246:247]
	global_load_dword v249, v[246:247], off
